# NSA sweeps: per-tile K prefetch addresses from one loop-invariant row pointer + immediate offsets (8 VALU -> 1 per tile)
# speedup vs baseline: 1.0117x; 1.0020x over previous
.LBB0_281:
	s_or_b64 exec, exec, s[4:5]
	s_waitcnt vmcnt(0)
	v_mul_f32_e32 v34, 0xbfb8aa3b, v116
	v_exp_f32_e32 v34, v34
	v_or_b32_e32 v0, v41, v43
	v_bitop3_b16 v0, v0, v47, v46 bitop3:0xfe
	v_bitop3_b16 v0, v0, v44, v42 bitop3:0xfe
	v_add_f32_e32 v34, 1.0, v34
	v_div_scale_f32 v35, s[4:5], v34, v34, 1.0
	v_rcp_f32_e32 v36, v35
	v_bitop3_b16 v0, v0, v40, v38 bitop3:0xfe
	v_lshlrev_b32_e32 v121, 2, v60
	v_add_u32_e32 v125, 0x10000, v121
	v_fma_f32 v37, -v35, v36, 1.0
	v_fmac_f32_e32 v36, v37, v36
	v_div_scale_f32 v37, vcc, 1.0, v34, 1.0
	v_mul_f32_e32 v39, v37, v36
	v_fma_f32 v41, -v35, v39, v37
	v_fmac_f32_e32 v39, v41, v36
	v_fma_f32 v35, -v35, v39, v37
	v_div_fmas_f32 v35, v35, v36, v39
	v_div_fixup_f32 v34, v35, v34, 1.0
	v_add_u32_e32 v35, 0x13280, v60
	ds_write_b8 v35, v0
	v_lshl_add_u32 v0, v61, 3, v205
	s_waitcnt lgkmcnt(0)
	s_barrier
	ds_read_b64 v[128:129], v0
	v_mul_f32_e32 v0, v34, v2
	v_mul_f32_e32 v3, v34, v3
	v_mul_f32_e32 v2, v34, v18
	ds_write2st64_b32 v121, v0, v3 offset0:144 offset1:148
	v_mul_f32_e32 v0, v34, v19
	ds_write2st64_b32 v121, v2, v0 offset0:208 offset1:212
	v_mul_f32_e32 v0, v34, v4
	v_mul_f32_e32 v3, v34, v5
	v_mul_f32_e32 v2, v34, v20
	ds_write2st64_b32 v121, v0, v3 offset0:152 offset1:156
	v_mul_f32_e32 v0, v34, v21
	ds_write2st64_b32 v121, v2, v0 offset0:216 offset1:220
	v_mul_f32_e32 v0, v34, v6
	v_mul_f32_e32 v3, v34, v7
	v_mul_f32_e32 v2, v34, v22
	ds_write2st64_b32 v121, v0, v3 offset0:160 offset1:164
	v_mul_f32_e32 v0, v34, v23
	ds_write2st64_b32 v121, v2, v0 offset0:224 offset1:228
	v_mul_f32_e32 v0, v34, v8
	v_mul_f32_e32 v3, v34, v9
	v_mul_f32_e32 v2, v34, v24
	ds_write2st64_b32 v121, v0, v3 offset0:168 offset1:172
	v_mul_f32_e32 v0, v34, v25
	ds_write2st64_b32 v121, v2, v0 offset0:232 offset1:236
	v_mul_f32_e32 v0, v34, v10
	v_mul_f32_e32 v3, v34, v11
	v_mul_f32_e32 v2, v34, v26
	ds_write2st64_b32 v121, v0, v3 offset0:176 offset1:180
	v_mul_f32_e32 v0, v34, v27
	ds_write2st64_b32 v121, v2, v0 offset0:240 offset1:244
	v_mul_f32_e32 v0, v34, v12
	v_mul_f32_e32 v3, v34, v13
	v_mul_f32_e32 v2, v34, v28
	ds_write2st64_b32 v121, v0, v3 offset0:184 offset1:188
	v_mul_f32_e32 v0, v34, v29
	ds_write2st64_b32 v121, v2, v0 offset0:248 offset1:252
	v_mul_f32_e32 v2, v34, v30
	v_mul_f32_e32 v0, v34, v14
	ds_write_b32 v125, v2
	v_mul_f32_e32 v2, v34, v15
	ds_write2st64_b32 v121, v0, v2 offset0:192 offset1:196
	v_mul_f32_e32 v0, v34, v31
	v_add_u32_e32 v127, 0x10400, v121
	v_mul_f32_e32 v2, v34, v32
	v_add_u32_e32 v135, 0x10800, v121
	ds_write_b32 v127, v0
	v_mul_f32_e32 v0, v34, v16
	ds_write_b32 v135, v2
	v_mul_f32_e32 v2, v34, v17
	s_or_b32 s11, s12, s11
	ds_write2st64_b32 v121, v0, v2 offset0:200 offset1:204
	v_mul_f32_e32 v0, v34, v33
	v_add_u32_e32 v152, 0x10c00, v121
	v_mov_b32_e32 v2, v133
	ds_write_b32 v152, v0
	s_lshl_b32 s6, s11, 19
	v_readlane_b32 s4, v253, 25
	s_add_u32 s4, s4, s6
	v_ashrrev_i32_e32 v158, 3, v2
	v_add_u32_e32 v0, 0x100, v2
	v_readlane_b32 s5, v253, 26
	v_ashrrev_i32_e32 v160, 3, v0
	v_ashrrev_i32_e32 v159, 31, v158
	v_lshlrev_b32_e32 v0, 3, v2
	s_addc_u32 s5, s5, 0
	v_readlane_b32 s7, v253, 27
	v_lshlrev_b64 v[4:5], 7, v[158:159]
	v_and_b32_e32 v20, 56, v0
	v_ashrrev_i32_e32 v161, 31, v160
	s_add_u32 s6, s7, s6
	v_readlane_b32 s7, v253, 28
	v_lshl_add_u64 v[4:5], s[4:5], 0, v[4:5]
	v_lshlrev_b32_e32 v0, 1, v20
	v_lshlrev_b64 v[8:9], 7, v[160:161]
	s_addc_u32 s7, s7, 0
	v_lshl_add_u64 v[4:5], v[4:5], 0, v[0:1]
	v_lshl_add_u64 v[8:9], s[4:5], 0, v[8:9]
	v_lshlrev_b64 v[12:13], 13, v[158:159]
	global_load_dwordx4 v[4:7], v[4:5], off
	v_lshl_add_u64 v[8:9], v[8:9], 0, v[0:1]
	v_lshl_add_u64 v[12:13], s[6:7], 0, v[12:13]
	v_lshlrev_b64 v[16:17], 13, v[160:161]
	global_load_dwordx4 v[8:11], v[8:9], off
	v_lshl_add_u64 v[162:163], v[12:13], 0, v[0:1]
	v_lshl_add_u64 v[16:17], s[6:7], 0, v[16:17]
	global_load_dwordx4 v[12:15], v[162:163], off
	v_lshl_add_u64 v[164:165], v[16:17], 0, v[0:1]
	global_load_dwordx4 v[16:19], v[164:165], off
	v_mad_u64_u32 v[166:167], s[6:7], v158, s21, v[20:21]
	v_lshlrev_b32_e32 v3, 1, v166
	v_mad_u64_u32 v[168:169], s[6:7], v160, s21, v[20:21]
	s_waitcnt lgkmcnt(0)
	s_barrier
	s_mov_b32 s12, 0
	s_cmp_lt_i32 s10, 0
	s_waitcnt vmcnt(3)
	ds_write_b128 v3, v[4:7]
	v_lshlrev_b32_e32 v4, 1, v168
	s_waitcnt vmcnt(2)
	ds_write_b128 v4, v[8:11]
	s_waitcnt vmcnt(1)
	ds_write_b128 v3, v[12:15] offset:9216
	s_waitcnt vmcnt(0)
	ds_write_b128 v4, v[16:19] offset:9216
	s_waitcnt lgkmcnt(0)
	s_barrier
	s_cbranch_scc1 .LBB0_298
	v_lshl_add_u64 v[170:171], s[4:5], 0, v[0:1]
	v_bfe_u32 v0, v2, 5, 1
	v_and_b32_e32 v116, 31, v2
	v_lshlrev_b32_e32 v131, 4, v0
	v_lshlrev_b32_e32 v2, 2, v0
	v_lshlrev_b32_e32 v0, 3, v0
	v_mov_b32_e32 v14, v1
	v_mov_b32_e32 v15, v1
	v_sub_u32_e32 v159, v126, v2
	v_sub_u32_e32 v161, 0, v0
	v_mov_b32_e32 v0, v1
	v_mov_b32_e32 v2, v1
	v_mov_b32_e32 v3, v1
	v_mov_b32_e32 v4, v1
	v_mov_b32_e32 v5, v1
	v_mov_b32_e32 v6, v1
	v_mov_b32_e32 v7, v1
	v_mov_b32_e32 v8, v1
	v_mov_b32_e32 v9, v1
	v_mov_b32_e32 v10, v1
	v_mov_b32_e32 v11, v1
	v_mov_b32_e32 v12, v1
	v_mov_b32_e32 v13, v1
	v_mov_b64_e32 v[30:31], v[14:15]
	v_mov_b64_e32 v[46:47], v[14:15]
	v_mul_u32_u24_e32 v156, 0x48, v116
	v_mov_b32_e32 v167, 0xf149f2ca
	v_mov_b32_e32 v169, 0
	v_mov_b64_e32 v[28:29], v[12:13]
	v_mov_b64_e32 v[26:27], v[10:11]
	v_mov_b64_e32 v[24:25], v[8:9]
	v_mov_b64_e32 v[22:23], v[6:7]
	v_mov_b64_e32 v[20:21], v[4:5]
	v_mov_b64_e32 v[18:19], v[2:3]
	v_mov_b64_e32 v[16:17], v[0:1]
	v_mov_b64_e32 v[44:45], v[12:13]
	v_mov_b64_e32 v[42:43], v[10:11]
	v_mov_b64_e32 v[40:41], v[8:9]
	v_mov_b64_e32 v[38:39], v[6:7]
	v_mov_b64_e32 v[36:37], v[4:5]
	v_mov_b64_e32 v[34:35], v[2:3]
	v_mov_b64_e32 v[32:33], v[0:1]
	v_lshrrev_b32_e32 v217, 1, v116
	v_xor_b32_e32 v217, v217, v116
	v_and_b32_e32 v217, 4, v217
	v_lshl_add_u32 v217, v217, 1, v217
	v_xor_b32_e32 v217, v217, v116
	s_movk_i32 s4, 0x80
	v_mad_u64_u32 v[190:191], vcc, v158, s4, v[170:171]
	s_mov_b64 s[6:7], 0x800
	v_lshl_add_u64 v[190:191], v[190:191], 0, s[6:7]
.LBB0_283:
	s_add_i32 s13, s12, 1
	s_min_i32 s4, s13, s10
	s_lshl_b32 s96, s4, 6
	s_lshl_b64 s[6:7], s[96:97], 7
	s_lshl_b64 s[4:5], s[96:97], 1
	v_lshl_add_u64 v[2:3], v[190:191], 0, s[6:7]
	global_load_dwordx4 v[8:11], v[2:3], off offset:-2048
	s_nop 0
	global_load_dwordx4 v[4:7], v[2:3], off offset:2048
	v_lshl_add_u64 v[2:3], v[162:163], 0, s[4:5]
	v_lshl_add_u64 v[48:49], v[164:165], 0, s[4:5]
	global_load_dwordx4 v[12:15], v[2:3], off
	global_load_dwordx4 v[112:115], v[48:49], off
	s_and_b32 s14, s12, 1
	s_mul_i32 s4, s14, 0x4800
	v_lshrrev_b64 v[2:3], s12, v[128:129]
	s_lshl_b32 s15, s12, 6
	v_and_b32_e32 v0, 1, v2
	s_or_b32 s5, s15, 63
	v_or_b32_e32 v3, s4, v131
	v_cmp_eq_u64_e64 s[38:39], 0, v[0:1]
	s_cmp_gt_i32 s5, s8
	v_add_u32_e32 v172, v3, v161
	s_mov_b64 s[4:5], -1
	s_cbranch_scc1 .LBB0_289
	v_mad_u32_u24 v0, v217, s37, v3
	v_lshl_add_u32 v215, v156, 1, v3
	ds_read_b128 v[220:223], v0
	ds_read_b128 v[236:239], v0 offset:4608
	ds_read_b128 v[224:227], v0 offset:32
	ds_read_b128 v[240:243], v0 offset:4640
	ds_read_b128 v[228:231], v0 offset:64
	ds_read_b128 v[244:247], v0 offset:4672
	ds_read_b128 v[232:235], v0 offset:96
	ds_read_b128 v[248:251], v0 offset:4704
	ds_read_b128 v[64:67], v215 offset:9216
	ds_read_b128 v[68:71], v215 offset:13824
	ds_read_b128 v[72:75], v215 offset:9248
	ds_read_b128 v[76:79], v215 offset:13856
	s_waitcnt lgkmcnt(11)
	v_mfma_f32_32x32x16_bf16 v[80:95], v[220:223], v[96:99], 0
	s_waitcnt lgkmcnt(10)
	v_mfma_f32_32x32x16_bf16 v[48:63], v[236:239], v[96:99], 0
	s_waitcnt lgkmcnt(9)
	v_mfma_f32_32x32x16_bf16 v[80:95], v[224:227], v[100:103], v[80:95]
	s_waitcnt lgkmcnt(8)
	v_mfma_f32_32x32x16_bf16 v[48:63], v[240:243], v[100:103], v[48:63]
	s_waitcnt lgkmcnt(7)
	v_mfma_f32_32x32x16_bf16 v[80:95], v[228:231], v[104:107], v[80:95]
	s_waitcnt lgkmcnt(6)
	v_mfma_f32_32x32x16_bf16 v[48:63], v[244:247], v[104:107], v[48:63]
	s_waitcnt lgkmcnt(5)
	v_mfma_f32_32x32x16_bf16 v[80:95], v[232:235], v[108:111], v[80:95]
	s_waitcnt lgkmcnt(4)
	v_mfma_f32_32x32x16_bf16 v[48:63], v[248:251], v[108:111], v[48:63]
	ds_read_b128 v[220:223], v215 offset:9280
	ds_read_b128 v[224:227], v215 offset:13888
	ds_read_b128 v[228:231], v215 offset:9312
	ds_read_b128 v[232:235], v215 offset:13920
	s_nop 7
	v_max3_f32 v0, v80, v81, v82
	v_max3_f32 v2, v88, v89, v90
	v_max3_f32 v0, v0, v83, v84
	v_max3_f32 v2, v2, v91, v92
	v_max3_f32 v0, v0, v85, v86
	v_max3_f32 v2, v2, v93, v94
	v_max3_f32 v0, v0, v87, v95
	v_max_f32_e32 v0, v0, v2
	v_cndmask_b32_e64 v0, v0, v202, s[38:39]
	ds_bpermute_b32 v2, v119, v0
	s_waitcnt lgkmcnt(0)
	v_max3_f32 v173, v167, v0, v2
	v_sub_f32_e32 v0, v167, v173
	v_exp_f32_e32 v0, v0
	v_cmp_eq_f32_e32 vcc, v173, v167
	s_cmp_eq_u64 vcc, exec
	s_cbranch_scc1 .Lnsw_keep0
	v_pk_mul_f32 v[46:47], v[46:47], v[0:1] op_sel_hi:[1,0]
	v_pk_mul_f32 v[44:45], v[44:45], v[0:1] op_sel_hi:[1,0]
	v_pk_mul_f32 v[42:43], v[42:43], v[0:1] op_sel_hi:[1,0]
	v_pk_mul_f32 v[40:41], v[40:41], v[0:1] op_sel_hi:[1,0]
	v_pk_mul_f32 v[38:39], v[38:39], v[0:1] op_sel_hi:[1,0]
	v_pk_mul_f32 v[36:37], v[36:37], v[0:1] op_sel_hi:[1,0]
	v_pk_mul_f32 v[34:35], v[34:35], v[0:1] op_sel_hi:[1,0]
	v_pk_mul_f32 v[32:33], v[32:33], v[0:1] op_sel_hi:[1,0]
	v_pk_mul_f32 v[30:31], v[30:31], v[0:1] op_sel_hi:[1,0]
	v_pk_mul_f32 v[28:29], v[28:29], v[0:1] op_sel_hi:[1,0]
	v_pk_mul_f32 v[26:27], v[26:27], v[0:1] op_sel_hi:[1,0]
	v_pk_mul_f32 v[24:25], v[24:25], v[0:1] op_sel_hi:[1,0]
	v_pk_mul_f32 v[22:23], v[22:23], v[0:1] op_sel_hi:[1,0]
	v_pk_mul_f32 v[20:21], v[20:21], v[0:1] op_sel_hi:[1,0]
	v_pk_mul_f32 v[18:19], v[18:19], v[0:1] op_sel_hi:[1,0]
	v_pk_mul_f32 v[16:17], v[16:17], v[0:1] op_sel_hi:[1,0]

.LBB0_299:
	v_mul_f32_e32 v0, 0xbfb8aa3b, v117
	v_exp_f32_e32 v0, v0
	s_lshl_b32 s4, s11, 18
	s_sub_i32 s5, 0xde1, s9
	s_max_i32 s12, s5, 0
	v_add_f32_e32 v0, 1.0, v0
	v_div_scale_f32 v3, s[6:7], v0, v0, 1.0
	v_rcp_f32_e32 v4, v3
	v_readlane_b32 s5, v253, 30
	v_fma_f32 v5, -v3, v4, 1.0
	v_fmac_f32_e32 v4, v5, v4
	v_div_scale_f32 v5, vcc, 1.0, v0, 1.0
	v_mul_f32_e32 v6, v5, v4
	v_fma_f32 v7, -v3, v6, v5
	v_fmac_f32_e32 v6, v7, v4
	v_fma_f32 v3, -v3, v6, v5
	v_div_fmas_f32 v3, v3, v4, v6
	v_div_fixup_f32 v0, v3, v0, 1.0
	ds_bpermute_b32 v3, v119, v2
	s_waitcnt lgkmcnt(0)
	v_add_f32_e32 v2, v2, v3
	v_div_scale_f32 v3, s[6:7], v2, v2, v0
	v_rcp_f32_e32 v4, v3
	s_lshl_b32 s6, s4, 1
	v_readlane_b32 s4, v253, 29
	s_add_u32 s4, s4, s6
	v_fma_f32 v5, -v3, v4, 1.0
	v_fmac_f32_e32 v4, v5, v4
	v_div_scale_f32 v5, vcc, v0, v2, v0
	v_mul_f32_e32 v6, v5, v4
	v_fma_f32 v7, -v3, v6, v5
	v_fmac_f32_e32 v6, v7, v4
	v_fma_f32 v3, -v3, v6, v5
	v_div_fmas_f32 v3, v3, v4, v6
	v_div_fixup_f32 v0, v3, v2, v0
	ds_read2st64_b32 v[2:3], v121 offset0:144 offset1:148
	ds_read2st64_b32 v[4:5], v121 offset0:208 offset1:212
	s_addc_u32 s5, s5, 0
	v_readlane_b32 s7, v253, 31
	s_add_u32 s6, s7, s6
	s_waitcnt lgkmcnt(1)
	v_fma_f32 v2, v64, v0, v2
	v_fmac_f32_e32 v3, v65, v0
	ds_write2st64_b32 v121, v2, v3 offset0:144 offset1:148
	ds_read2st64_b32 v[2:3], v121 offset0:152 offset1:156
	s_waitcnt lgkmcnt(2)
	v_fma_f32 v4, v48, v0, v4
	v_fmac_f32_e32 v5, v49, v0
	ds_write2st64_b32 v121, v4, v5 offset0:208 offset1:212
	ds_read2st64_b32 v[4:5], v121 offset0:216 offset1:220
	s_waitcnt lgkmcnt(2)
	v_fma_f32 v2, v66, v0, v2
	v_fmac_f32_e32 v3, v67, v0
	ds_write2st64_b32 v121, v2, v3 offset0:152 offset1:156
	ds_read2st64_b32 v[2:3], v121 offset0:160 offset1:164
	s_waitcnt lgkmcnt(2)
	v_fma_f32 v4, v50, v0, v4
	v_fmac_f32_e32 v5, v51, v0
	ds_write2st64_b32 v121, v4, v5 offset0:216 offset1:220
	ds_read2st64_b32 v[4:5], v121 offset0:224 offset1:228
	s_waitcnt lgkmcnt(2)
	v_fma_f32 v2, v68, v0, v2
	v_fmac_f32_e32 v3, v69, v0
	ds_write2st64_b32 v121, v2, v3 offset0:160 offset1:164
	ds_read2st64_b32 v[2:3], v121 offset0:168 offset1:172
	s_waitcnt lgkmcnt(2)
	v_fma_f32 v4, v52, v0, v4
	v_fmac_f32_e32 v5, v53, v0
	ds_write2st64_b32 v121, v4, v5 offset0:224 offset1:228
	ds_read2st64_b32 v[4:5], v121 offset0:232 offset1:236
	s_waitcnt lgkmcnt(2)
	v_fma_f32 v2, v70, v0, v2
	v_fmac_f32_e32 v3, v71, v0
	ds_write2st64_b32 v121, v2, v3 offset0:168 offset1:172
	ds_read2st64_b32 v[2:3], v121 offset0:176 offset1:180
	s_waitcnt lgkmcnt(2)
	v_fma_f32 v4, v54, v0, v4
	v_fmac_f32_e32 v5, v55, v0
	ds_write2st64_b32 v121, v4, v5 offset0:232 offset1:236
	ds_read2st64_b32 v[4:5], v121 offset0:240 offset1:244
	s_waitcnt lgkmcnt(2)
	v_fma_f32 v2, v72, v0, v2
	v_fmac_f32_e32 v3, v73, v0
	ds_write2st64_b32 v121, v2, v3 offset0:176 offset1:180
	ds_read2st64_b32 v[2:3], v121 offset0:184 offset1:188
	s_waitcnt lgkmcnt(2)
	v_fma_f32 v4, v56, v0, v4
	v_fmac_f32_e32 v5, v57, v0
	ds_write2st64_b32 v121, v4, v5 offset0:240 offset1:244
	ds_read2st64_b32 v[4:5], v121 offset0:248 offset1:252
	s_waitcnt lgkmcnt(2)
	v_fma_f32 v2, v74, v0, v2
	v_fmac_f32_e32 v3, v75, v0
	ds_write2st64_b32 v121, v2, v3 offset0:184 offset1:188
	ds_read2st64_b32 v[2:3], v121 offset0:192 offset1:196
	s_waitcnt lgkmcnt(2)
	v_fma_f32 v4, v58, v0, v4
	v_fmac_f32_e32 v5, v59, v0
	ds_write2st64_b32 v121, v4, v5 offset0:248 offset1:252
	ds_read_b32 v4, v125
	s_waitcnt lgkmcnt(2)
	v_fma_f32 v2, v76, v0, v2
	v_fmac_f32_e32 v3, v77, v0
	ds_write2st64_b32 v121, v2, v3 offset0:192 offset1:196
	ds_read_b32 v2, v127
	s_waitcnt lgkmcnt(2)
	v_fmac_f32_e32 v4, v60, v0
	ds_write_b32 v125, v4
	ds_read_b32 v4, v135
	v_readlane_b32 s7, v253, 32
	s_waitcnt lgkmcnt(2)
	v_fmac_f32_e32 v2, v61, v0
	ds_write_b32 v127, v2
	ds_read2st64_b32 v[2:3], v121 offset0:200 offset1:204
	v_mov_b32_e32 v6, v133
	s_addc_u32 s7, s7, 0
	s_lshr_b32 s11, s12, 6
	s_and_b32 s12, s12, 0x3ffffc0
	s_waitcnt lgkmcnt(0)
	v_fma_f32 v2, v78, v0, v2
	v_fmac_f32_e32 v3, v79, v0
	ds_write2st64_b32 v121, v2, v3 offset0:200 offset1:204
	ds_read_b32 v2, v152
	v_fmac_f32_e32 v4, v62, v0
	ds_write_b32 v135, v4
	s_lshl_b32 s96, s12, 1
	s_cmp_gt_i32 s11, s10
	s_waitcnt lgkmcnt(1)
	v_fmac_f32_e32 v2, v63, v0
	ds_write_b32 v152, v2
	s_nop 0
	v_ashrrev_i32_e32 v116, 3, v6
	v_add_u32_e32 v0, 0x100, v6
	v_add_u32_e32 v2, s12, v116
	v_ashrrev_i32_e32 v128, 3, v0
	v_ashrrev_i32_e32 v3, 31, v2
	v_lshlrev_b32_e32 v0, 3, v6
	v_lshlrev_b64 v[2:3], 7, v[2:3]
	v_and_b32_e32 v24, 56, v0
	v_lshl_add_u64 v[2:3], s[4:5], 0, v[2:3]
	v_lshlrev_b32_e32 v0, 1, v24
	v_lshl_add_u64 v[2:3], v[2:3], 0, v[0:1]
	global_load_dwordx4 v[8:11], v[2:3], off
	v_add_u32_e32 v2, s12, v128
	v_ashrrev_i32_e32 v3, 31, v2
	v_lshlrev_b64 v[2:3], 7, v[2:3]
	v_lshl_add_u64 v[2:3], s[4:5], 0, v[2:3]
	v_lshl_add_u64 v[2:3], v[2:3], 0, v[0:1]
	v_ashrrev_i32_e32 v117, 31, v116
	global_load_dwordx4 v[12:15], v[2:3], off
	v_lshlrev_b64 v[2:3], 13, v[116:117]
	v_lshl_add_u64 v[2:3], s[6:7], 0, v[2:3]
	v_lshl_add_u64 v[4:5], v[2:3], 0, s[96:97]
	v_lshl_add_u64 v[4:5], v[4:5], 0, v[0:1]
	v_ashrrev_i32_e32 v129, 31, v128
	global_load_dwordx4 v[16:19], v[4:5], off
	v_lshlrev_b64 v[4:5], 13, v[128:129]
	v_lshl_add_u64 v[4:5], s[6:7], 0, v[4:5]
	v_lshl_add_u64 v[20:21], v[4:5], 0, s[96:97]
	v_lshl_add_u64 v[20:21], v[20:21], 0, v[0:1]
	global_load_dwordx4 v[20:23], v[20:21], off
	v_mad_u64_u32 v[158:159], s[6:7], v116, s21, v[24:25]
	v_lshlrev_b32_e32 v7, 1, v158
	v_mad_u64_u32 v[160:161], s[6:7], v128, s21, v[24:25]
	s_waitcnt lgkmcnt(0)
	s_barrier
	s_waitcnt vmcnt(3)
	ds_write_b128 v7, v[8:11]
	v_lshlrev_b32_e32 v8, 1, v160
	s_waitcnt vmcnt(2)
	ds_write_b128 v8, v[12:15]
	s_waitcnt vmcnt(1)
	ds_write_b128 v7, v[16:19] offset:9216
	s_waitcnt vmcnt(0)
	ds_write_b128 v8, v[20:23] offset:9216
	s_waitcnt lgkmcnt(0)
	s_barrier
	s_cbranch_scc1 .LBB0_316
	v_lshl_add_u64 v[162:163], s[4:5], 0, v[0:1]
	v_lshl_add_u64 v[164:165], v[2:3], 0, v[0:1]
	v_lshl_add_u64 v[166:167], v[4:5], 0, v[0:1]
	v_bfe_u32 v0, v6, 5, 1
	v_lshlrev_b32_e32 v129, 4, v0
	v_lshlrev_b32_e32 v131, 2, v0
	v_lshlrev_b32_e32 v0, 3, v0
	v_mov_b32_e32 v14, v1
	v_mov_b32_e32 v15, v1
	v_and_b32_e32 v117, 31, v6
	v_sub_u32_e32 v161, 0, v0
	v_mov_b32_e32 v0, v1
	v_mov_b32_e32 v2, v1
	v_mov_b32_e32 v3, v1
	v_mov_b32_e32 v4, v1
	v_mov_b32_e32 v5, v1
	v_mov_b32_e32 v6, v1
	v_mov_b32_e32 v7, v1
	v_mov_b32_e32 v8, v1
	v_mov_b32_e32 v9, v1
	v_mov_b32_e32 v10, v1
	v_mov_b32_e32 v11, v1
	v_mov_b32_e32 v12, v1
	v_mov_b32_e32 v13, v1
	v_mov_b64_e32 v[30:31], v[14:15]
	v_mov_b64_e32 v[46:47], v[14:15]
	s_sub_i32 s9, 0xdff, s9
	v_add_u32_e32 v156, 0xfffffe00, v126
	v_mul_u32_u24_e32 v159, 0x48, v117
	v_mov_b32_e32 v168, 0xf149f2ca
	v_mov_b32_e32 v169, 0
	v_mov_b64_e32 v[28:29], v[12:13]
	v_mov_b64_e32 v[26:27], v[10:11]
	v_mov_b64_e32 v[24:25], v[8:9]
	v_mov_b64_e32 v[22:23], v[6:7]
	v_mov_b64_e32 v[20:21], v[4:5]
	v_mov_b64_e32 v[18:19], v[2:3]
	v_mov_b64_e32 v[16:17], v[0:1]
	v_mov_b64_e32 v[44:45], v[12:13]
	v_mov_b64_e32 v[42:43], v[10:11]
	v_mov_b64_e32 v[40:41], v[8:9]
	v_mov_b64_e32 v[38:39], v[6:7]
	v_mov_b64_e32 v[36:37], v[4:5]
	v_mov_b64_e32 v[34:35], v[2:3]
	v_mov_b64_e32 v[32:33], v[0:1]
	s_mov_b32 s12, s11
	v_lshrrev_b32_e32 v218, 1, v117
	v_xor_b32_e32 v218, v218, v117
	v_and_b32_e32 v218, 4, v218
	v_lshl_add_u32 v218, v218, 1, v218
	v_xor_b32_e32 v218, v218, v117
	s_movk_i32 s4, 0x80
	v_mad_u64_u32 v[190:191], vcc, v116, s4, v[162:163]
	s_mov_b64 s[6:7], 0x800
	v_lshl_add_u64 v[190:191], v[190:191], 0, s[6:7]
.LBB0_301:
	s_add_i32 s13, s12, 1
	s_min_i32 s4, s13, s10
	s_lshl_b32 s4, s4, 6
	s_ashr_i32 s5, s4, 31
	s_lshl_b64 s[6:7], s[4:5], 7
	s_lshl_b64 s[4:5], s[4:5], 1
	v_lshl_add_u64 v[14:15], v[190:191], 0, s[6:7]
	v_lshl_add_u64 v[10:11], v[164:165], 0, s[4:5]
	global_load_dwordx4 v[6:9], v[14:15], off offset:-2048
	s_nop 0
	global_load_dwordx4 v[2:5], v[14:15], off offset:2048
	v_lshl_add_u64 v[14:15], v[166:167], 0, s[4:5]
	global_load_dwordx4 v[10:13], v[10:11], off
	s_nop 0
	global_load_dwordx4 v[112:115], v[14:15], off
	s_sub_i32 s4, s12, s11
	s_lshl_b32 s6, s12, 6
	s_and_b32 s14, s4, 1
	s_or_b32 s4, s6, 63
	s_cmp_le_i32 s4, s8
	s_cselect_b64 s[4:5], -1, 0
	s_cmp_gt_i32 s6, s9
	s_mul_i32 s7, s14, 0x4800
	s_cselect_b64 s[16:17], -1, 0
	s_and_b64 s[16:17], s[4:5], s[16:17]
	v_or_b32_e32 v14, s7, v129
	s_mov_b64 s[4:5], -1
	s_and_b64 vcc, exec, s[16:17]
	v_add_u32_e32 v15, v14, v161
	s_cbranch_vccnz .LBB0_307
	v_mov_b64_e32 v[78:79], v[30:31]
	v_mov_b64_e32 v[62:63], v[46:47]
	v_or_b32_e32 v171, s6, v131
	s_mov_b32 s6, 0
	v_mov_b64_e32 v[76:77], v[28:29]
	v_mov_b64_e32 v[74:75], v[26:27]
	v_mov_b64_e32 v[72:73], v[24:25]
	v_mov_b64_e32 v[70:71], v[22:23]
	v_mov_b64_e32 v[68:69], v[20:21]
	v_mov_b64_e32 v[66:67], v[18:19]
	v_mov_b64_e32 v[64:65], v[16:17]
	v_mov_b64_e32 v[60:61], v[44:45]
	v_mov_b64_e32 v[58:59], v[42:43]
	v_mov_b64_e32 v[56:57], v[40:41]
	v_mov_b64_e32 v[54:55], v[38:39]
	v_mov_b64_e32 v[52:53], v[36:37]
	v_mov_b64_e32 v[50:51], v[34:35]
	v_mov_b64_e32 v[48:49], v[32:33]
	v_mov_b32_e32 v172, v169
	v_mov_b32_e32 v170, v168
